# scan stage C: next-step operand LDS stores issued before the final MFMAs instead of at the step tail
# baseline (speedup 1.0000x reference)
.LBB0_1494:
	s_or_b64 exec, exec, s[2:3]
	v_cvt_pk_bf16_f32 v62, v64, v65
	v_cvt_pk_bf16_f32 v63, v60, v61
	ds_write_b64 v137, v[62:63]
	v_cvt_pk_bf16_f32 v60, v76, v77
	v_cvt_pk_bf16_f32 v61, v78, v79
	v_cvt_pk_bf16_f32 v62, v80, v81
	v_cvt_pk_bf16_f32 v63, v82, v83
	ds_write2_b64 v134, v[60:61], v[62:63] offset1:4
	v_cvt_pk_bf16_f32 v60, v84, v85
	v_cvt_pk_bf16_f32 v61, v86, v87
	v_cvt_pk_bf16_f32 v62, v88, v89
	v_cvt_pk_bf16_f32 v63, v90, v91
	ds_write2_b64 v134, v[60:61], v[62:63] offset0:8 offset1:12
	v_add_u32_e32 v60, v163, v160
	s_waitcnt lgkmcnt(0)
	s_barrier
	ds_read_b128 v[62:65], v60
	ds_read_b128 v[76:79], v132
	ds_read_b128 v[80:83], v133
	ds_read_b128 v[84:87], v60 offset:64
	s_waitcnt lgkmcnt(0)
	v_mfma_f32_16x16x32_bf16 v[76:79], v[62:65], v[76:79], 0
	v_add_u32_e32 v61, s64, v125
	ds_read_b128 v[240:243], v61
	s_and_b64 s[2:3], s[0:1], exec
	s_mov_b32 s2, 0x23100
	v_mfma_f32_16x16x32_bf16 v[62:65], v[62:65], v[80:83], 0
	ds_read_b128 v[80:83], v130
	ds_read_b128 v[88:91], v131
	s_cselect_b32 s2, s2, 0x8800
	s_waitcnt lgkmcnt(0)
	v_mfma_f32_16x16x32_bf16 v[76:79], v[84:87], v[80:83], v[76:79]
	ds_read_b128 v[80:83], v60 offset:128
	v_mfma_f32_16x16x32_bf16 v[62:65], v[84:87], v[88:91], v[62:65]
	ds_read_b128 v[84:87], v128
	ds_read_b128 v[88:91], v129
	s_waitcnt lgkmcnt(0)
	v_mfma_f32_16x16x32_bf16 v[76:79], v[80:83], v[84:87], v[76:79]
	ds_read_b128 v[84:87], v60 offset:192
	v_mfma_f32_16x16x32_bf16 v[62:65], v[80:83], v[88:91], v[62:65]
	ds_read_b128 v[80:83], v126
	ds_read_b128 v[88:91], v127
	s_waitcnt lgkmcnt(0)
	v_mfma_f32_16x16x32_bf16 v[76:79], v[84:87], v[80:83], v[76:79]
	s_waitcnt lgkmcnt(0)
	v_sub_f32_e32 v61, v194, v240
	v_mul_f32_e32 v61, 0x3fb8aa3b, v61
	v_exp_f32_e32 v80, v61
	v_sub_f32_e32 v61, v194, v241
	v_mul_f32_e32 v61, 0x3fb8aa3b, v61
	v_exp_f32_e32 v81, v61
	v_sub_f32_e32 v61, v194, v242
	v_mul_f32_e32 v61, 0x3fb8aa3b, v61
	v_exp_f32_e32 v82, v61
	v_sub_f32_e32 v61, v194, v243
	v_mul_f32_e32 v61, 0x3fb8aa3b, v61
	v_mfma_f32_16x16x32_bf16 v[64:67], v[84:87], v[88:91], v[62:65]
	v_exp_f32_e32 v83, v61
	v_sub_f32_e32 v73, v73, v77
	v_sub_f32_e32 v72, v72, v76
	v_sub_f32_e32 v63, v75, v79
	v_sub_f32_e32 v62, v74, v78
	v_pk_mul_f32 v[74:75], v[72:73], v[80:81]
	v_pk_mul_f32 v[76:77], v[62:63], v[82:83]
	v_cvt_pk_bf16_f32 v72, v72, v73
	v_cvt_pk_bf16_f32 v73, v62, v63
	v_add_u32_e32 v62, v170, v164
	v_sub_f32_e32 v67, v71, v67
	v_sub_f32_e32 v66, v70, v66
	v_sub_f32_e32 v65, v69, v65
	v_sub_f32_e32 v64, v68, v64
	ds_write_b64 v62, v[72:73]
	v_cvt_pk_bf16_f32 v72, v74, v75
	v_cvt_pk_bf16_f32 v73, v76, v77
	v_pk_mul_f32 v[68:69], v[64:65], v[80:81]
	v_pk_mul_f32 v[70:71], v[66:67], v[82:83]
	v_cvt_pk_bf16_f32 v64, v64, v65
	v_cvt_pk_bf16_f32 v65, v66, v67
	v_add_u32_e32 v63, v171, v164
	ds_write_b64 v124, v[72:73]
	ds_write_b64 v63, v[64:65]
	v_cvt_pk_bf16_f32 v64, v68, v69
	v_cvt_pk_bf16_f32 v65, v70, v71
	ds_write_b64 v123, v[64:65]
	v_add_u32_e32 v64, v170, v160
	s_waitcnt lgkmcnt(0)
	s_barrier
	ds_read_b128 v[66:69], v64
	ds_read_b32 v244, v195
	v_add_u32_e32 v61, v162, v160
	v_add_u32_e32 v65, v171, v160
	v_mul_f32_e32 v86, 0x3fb8aa3b, v194
	ds_read_b128 v[70:73], v61
	ds_read_b128 v[74:77], v65
	ds_read_b128 v[78:81], v193
	ds_read_b128 v[82:85], v193 offset:2304
	v_exp_f32_e32 v90, v86
	ds_read_b128 v[86:89], v120
	s_waitcnt lgkmcnt(0)
	v_mfma_f32_16x16x32_bf16 v[66:69], v[66:69], v[70:73], 0
	v_mul_f32_e64 v2, v2, v90
	v_mul_f32_e64 v3, v3, v90
	v_pk_mul_f32 v[0:1], v[0:1], v[90:91] op_sel_hi:[1,0]
	v_pk_mul_f32 v[10:11], v[10:11], v[90:91] op_sel_hi:[1,0]
	v_mfma_f32_16x16x32_bf16 v[70:73], v[74:77], v[70:73], 0
	ds_read_b128 v[74:77], v193 offset:4608
	v_pk_mul_f32 v[8:9], v[8:9], v[90:91] op_sel_hi:[1,0]
	v_pk_mul_f32 v[6:7], v[6:7], v[90:91] op_sel_hi:[1,0]
	v_mfma_f32_16x16x32_bf16 v[0:3], v[78:81], v[86:89], v[0:3]
	ds_read_b128 v[78:81], v193 offset:6912
	v_pk_mul_f32 v[4:5], v[4:5], v[90:91] op_sel_hi:[1,0]
	v_pk_mul_f32 v[14:15], v[14:15], v[90:91] op_sel_hi:[1,0]
	v_pk_mul_f32 v[12:13], v[12:13], v[90:91] op_sel_hi:[1,0]
	v_mfma_f32_16x16x32_bf16 v[8:11], v[82:85], v[86:89], v[8:11]
	ds_read_b128 v[82:85], v122
	s_waitcnt lgkmcnt(0)
	v_mfma_f32_16x16x32_bf16 v[4:7], v[74:77], v[86:89], v[4:7]
	ds_read_b128 v[74:77], v61 offset:64
	v_mfma_f32_16x16x32_bf16 v[12:15], v[78:81], v[86:89], v[12:15]
	ds_read_b128 v[78:81], v121
	s_waitcnt lgkmcnt(0)
	v_mfma_f32_16x16x32_bf16 v[66:69], v[82:85], v[74:77], v[66:69]
	ds_read_b128 v[82:85], v193 offset:64
	ds_read_b128 v[86:89], v120 offset:64
	v_mfma_f32_16x16x32_bf16 v[70:73], v[78:81], v[74:77], v[70:73]
	ds_read_b128 v[74:77], v193 offset:2368
	ds_read_b128 v[78:81], v193 offset:4672
	s_waitcnt lgkmcnt(0)
	v_mfma_f32_16x16x32_bf16 v[8:11], v[74:77], v[86:89], v[8:11]
	ds_read_b128 v[74:77], v193 offset:6976
	v_mfma_f32_16x16x32_bf16 v[4:7], v[78:81], v[86:89], v[4:7]
	s_waitcnt lgkmcnt(0)
	s_waitcnt vmcnt(0)
	v_add_u32_e32 v245, s2, v165
	ds_write_b128 v150, v[16:19]
	ds_write_b128 v151, v[20:23] offset:17408
	v_add_u32_e32 v16, v245, v152
	ds_write_b128 v16, v[24:27]
	ds_write_b128 v153, v[28:31]
	ds_write_b128 v154, v[32:35] offset:17408
	v_add_u32_e32 v16, v245, v155
	ds_write_b128 v16, v[36:39]
	ds_write_b128 v156, v[40:43] offset:53248
	ds_write_b128 v156, v[44:47] offset:62464
	ds_write_b128 v157, v[48:51]
	v_mfma_f32_16x16x32_bf16 v[12:15], v[74:77], v[86:89], v[12:15]
	v_mul_f32_e32 v74, 0x3fb8aa3b, v244
	v_exp_f32_e32 v74, v74
	v_lshl_add_u32 v76, s63, 6, v93
	v_mfma_f32_16x16x32_bf16 v[0:3], v[82:85], v[86:89], v[0:3]
	v_ashrrev_i32_e32 v77, 31, v76
	v_lshlrev_b64 v[76:77], 10, v[76:77]
	v_pk_fma_f32 v[54:55], v[54:55], v[74:75], v[68:69] op_sel_hi:[1,0,1]
	v_pk_fma_f32 v[52:53], v[52:53], v[74:75], v[66:67] op_sel_hi:[1,0,1]
	v_pk_fma_f32 v[56:57], v[56:57], v[74:75], v[70:71] op_sel_hi:[1,0,1]
	v_cvt_pk_bf16_f32 v52, v52, v53
	v_cvt_pk_bf16_f32 v53, v54, v55
	v_lshl_add_u64 v[54:55], v[116:117], 0, v[76:77]
	s_waitcnt vmcnt(0)
	global_store_dwordx2 v[54:55], v[52:53], off
	v_pk_fma_f32 v[52:53], v[58:59], v[74:75], v[72:73] op_sel_hi:[1,0,1]
	v_cvt_pk_bf16_f32 v56, v56, v57
	v_cvt_pk_bf16_f32 v57, v52, v53
	v_cvt_pk_bf16_f32 v52, v0, v1
	v_cvt_pk_bf16_f32 v53, v2, v3
	global_store_dwordx2 v[54:55], v[56:57], off offset:32
	ds_write_b64 v119, v[52:53]
	v_cvt_pk_bf16_f32 v52, v8, v9
	v_cvt_pk_bf16_f32 v53, v10, v11
	ds_write_b64 v118, v[52:53]
	v_cvt_pk_bf16_f32 v52, v4, v5
	v_cvt_pk_bf16_f32 v53, v6, v7
	ds_write_b64 v111, v[52:53]
	v_cvt_pk_bf16_f32 v52, v12, v13
	v_cvt_pk_bf16_f32 v53, v14, v15
	ds_write_b64 v97, v[52:53]
	s_and_saveexec_b64 s[2:3], s[60:61]
	s_cbranch_execz .LBB0_1471
	s_and_b64 s[0:1], s[0:1], exec
	s_cselect_b32 s0, 0x27900, s89
	v_add_u32_e32 v16, s0, v158
	ds_write_b32 v16, v149
	s_branch .LBB0_1471
